# opt23: one static s_setprio 1 for waves 4-7 during the attention phase (reset at phase end)
# baseline (speedup 1.0000x reference)
; __device__ __forceinline__ void phase_attn(ArgsP a, int layer, unsigned char* lds) {
;     const Ids I = make_ids(); unsigned char* ws = ws_base(a);
;     ACtx X{(const half_t*)(ws + WS_PROJ), (const half_t*)(ws + WS_KC), (const half_t*)(ws + WS_VCT), (const half_t*)(ws + WS_VT), (const half_t*)(ws + WS_KF), (half_t*)(ws + WS_MIX), (float*)(ws + WS_LSE), a->sinks + layer * 6, ws + WS_KS8, ws + WS_VS8};
;     float* ldsw = (float*)lds + I.wave * 4416;
;     const int pb = I.gw >> 3;
;     const int vb = ((I.G & 7) == 0) ? (pb & 7) * (I.G >> 3) + (pb >> 3) : pb;
;     const int vgw = vb * 8 + (I.gw & 7);
.LBB0_683:
	s_or_b64 exec, exec, s[0:1]
	v_readlane_b32 s2, v253, 0
	v_readlane_b32 s3, v253, 1
	s_waitcnt lgkmcnt(0)
	v_mov_b32_e32 v2, v170
	s_barrier
	v_readfirstlane_b32 s100, v170
	s_lshr_b32 s100, s100, 8
	s_cmp_eq_u32 s100, 0
	s_cbranch_scc1 .Lattn_prio_skip
	s_setprio 1
.Lattn_prio_skip:
	s_load_dwordx2 s[6:7], s[2:3], 0x60
	v_readfirstlane_b32 s0, v2
	s_ashr_i32 s1, s0, 6
	s_lshl_b32 s4, s77, 3
	s_waitcnt lgkmcnt(0)
	v_writelane_b32 v253, s6, 30
	s_nop 1
	v_writelane_b32 v253, s7, 31
	s_load_dwordx2 s[6:7], s[2:3], 0x98
	s_add_i32 s2, s1, s4
	v_readlane_b32 s4, v253, 7
	v_readlane_b32 s5, v253, 8
	s_waitcnt lgkmcnt(0)
	s_andn2_b64 vcc, exec, s[4:5]
	v_writelane_b32 v253, s6, 32
	s_nop 1
	v_writelane_b32 v253, s7, 33
	s_cbranch_vccz .LBB0_685
	s_ashr_i32 s6, s2, 3
	s_branch .LBB0_686

; #define LAS __attribute__((address_space(3)))
; __device__ __forceinline__ unsigned xb_ld(unsigned* p)              { return __hip_atomic_load(p, __ATOMIC_RELAXED, __HIP_MEMORY_SCOPE_AGENT); }
; __device__ __forceinline__ unsigned xb_xcc_id() { return (unsigned)__builtin_amdgcn_s_getreg((3 << 11) | 20) & 0xFu; }
; __device__ __forceinline__ void xcd_barrier_complete(unsigned* bar, unsigned x, unsigned& nloc, unsigned& nx) {
;     ...
;         sum = 0u; cnt = 0u; mine = 0u;
; #pragma unroll
;         for (unsigned j = 0; j < 16; ++j) { const unsigned c = xb_ld(&bar[XB_XCNT(j)]); sum += c; cnt += (c > 0u) ? 1u : 0u; mine = (j == x) ? c : mine; }
; __device__ __forceinline__ void xcd_barrier(unsigned* bar, volatile LAS unsigned* st) {
;     asm volatile("s_waitcnt vmcnt(0)" ::: "memory");
;     __syncthreads();
;     if (threadIdx.x == 0) {
;         const unsigned x = xb_xcc_id();
;         __builtin_amdgcn_s_waitcnt(0);
;         unsigned nloc = st[0], nx = st[1];
;         if (nloc == 0u) { xcd_barrier_complete(bar, x, nloc, nx); st[0] = nloc; st[1] = nx; }
.LBB0_1038:
	s_setprio 0
	v_readlane_b32 s2, v253, 0
	v_readlane_b32 s3, v253, 1
	s_waitcnt vmcnt(0)
	s_waitcnt lgkmcnt(0)
	s_barrier
	s_mov_b64 s[0:1], exec
	v_readlane_b32 s4, v253, 5
	v_readlane_b32 s5, v253, 6
	s_and_b64 s[4:5], s[0:1], s[4:5]
	s_mov_b64 exec, s[4:5]
	s_cbranch_execz .LBB0_1090
	v_readlane_b32 s5, v253, 18
	s_load_dwordx2 s[2:3], s[2:3], 0x98
	s_getreg_b32 s4, hwreg(HW_REG_XCC_ID, 0, 4)
	v_mov_b32_e32 v0, s5
	s_waitcnt vmcnt(0) expcnt(0) lgkmcnt(0)
	ds_read_b32 v3, v0
	v_readlane_b32 s5, v253, 19
	s_and_b32 s33, s4, 15
	s_waitcnt lgkmcnt(0)
	v_cmp_ne_u32_e32 vcc, 0, v3
	v_mov_b32_e32 v0, s5
	ds_read_b32 v2, v0
	s_cbranch_vccnz .LBB0_1054
	s_add_u32 s4, s2, 0x1fa00200
	s_addc_u32 s5, s3, 0
	s_add_u32 s6, s2, 0x1fa00400
	s_addc_u32 s7, s3, 0
	s_add_u32 s8, s2, 0x1fa00500
	s_addc_u32 s9, s3, 0
	s_add_u32 s10, s2, 0x1fa00600
	s_addc_u32 s11, s3, 0
	s_add_u32 s12, s2, 0x1fa00700
	s_addc_u32 s13, s3, 0
	s_add_u32 s14, s2, 0x1fa00800
	s_addc_u32 s15, s3, 0
	s_add_u32 s16, s2, 0x1fa00900
	s_addc_u32 s17, s3, 0
	s_add_u32 s18, s2, 0x1fa00a00
	s_addc_u32 s19, s3, 0
	s_add_u32 s20, s2, 0x1fa00b00
	s_addc_u32 s21, s3, 0
	s_add_u32 s22, s2, 0x1fa00c00
	s_addc_u32 s23, s3, 0
	s_add_u32 s24, s2, 0x1fa00d00
	s_addc_u32 s25, s3, 0
	s_add_u32 s26, s2, 0x1fa00e00
	s_addc_u32 s27, s3, 0
	s_add_u32 s28, s2, 0x1fa00f00
	s_addc_u32 s29, s3, 0
	s_add_u32 s30, s2, 0x1fa01000
	s_addc_u32 s31, s3, 0
	s_add_u32 s34, s2, 0x1fa01100
	s_addc_u32 s35, s3, 0
	s_add_u32 s36, s2, 0x1fa01200
	s_addc_u32 s37, s3, 0
	s_add_u32 s38, s2, 0x1fa01300
	s_addc_u32 s39, s3, 0
	s_mov_b32 s46, 1
	s_branch .LBB0_1042
